# v054 + global attention: softmax stabilised with a launch-wide upper bound c on the scores (Cauchy-Schwarz from the q/k RMSNorm gains, computed once per launch) instead of the running row max when c<4
# baseline (speedup 1.0000x reference)
; #define LAS __attribute__((address_space(3)))
; __global__ void __launch_bounds__(512, 2) mega_fwd(Args a) {
;     ...
;     if (threadIdx.x == 0) ((volatile LAS unsigned*)(lds + LDS_XB))[4] = (__hip_atomic_load((unsigned*)(a.ws + WS_BAR) + XL_BAD, __ATOMIC_RELAXED, __HIP_MEMORY_SCOPE_AGENT) == 0u) ? 1u : 0u;
;     __syncthreads();
;     constexpr int NS = N_PER * NCH;
;     for (int step2 = 0; step2 < 2 * NS; ++step2) {
;         const int step = step2 >> 1;
;         const bool dup_ = ((PH_DUP >> (step % N_PER)) & 1);
;         if ((step2 & 1) && !dup_) continue;
;         STEP_LOCALS
;         const int xl_good = __builtin_amdgcn_readfirstlane((int)((volatile LAS unsigned*)(lds + LDS_XB))[4]);
;         const int xl_x = __builtin_amdgcn_readfirstlane((int)((volatile LAS unsigned*)(lds + LDS_XB))[2]), xl_r = __builtin_amdgcn_readfirstlane((int)((volatile LAS unsigned*)(lds + LDS_XB))[3]);
;         const int cx = xl_good ? (xl_x + 8 * xl_r) : bx;
;         {
;             const int c = step / N_PER, k = step % N_PER;
;             const bool prompt = c < NCH_P;
;     ...
;             const int S_ = prompt ? 8192 : 2048, nseq = CH / S_, NQB = S_ / 256;
;             const int memseq0 = prompt ? (CH / 8192) * c : 8 + (CH / 2048) * (c - NCH_P);
;             gfloat* const ssq1 = ssq; gfloat* const ssq2 = ssq + CH * 4; gfloat* const ssq3 = ssq + 2 * CH * 4;
.LBB0_284:
	s_or_b64 exec, exec, s[0:1]
	s_ashr_i32 s1, s92, 31
	s_lshr_b32 s1, s1, 29
	s_add_i32 s1, s92, s1
	s_ashr_i32 s3, s1, 3
	s_and_b32 s1, s1, -8
	s_ashr_i32 s0, s14, 3
	s_sub_i32 s1, s92, s1
	s_mul_i32 s0, s0, s1
	s_add_i32 s3, s0, s3
	s_ashr_i32 s13, s14, 31
	s_lshl_b32 s50, s14, 1
	s_add_u32 s0, s6, 0x3c58a200
	s_addc_u32 s1, s7, 0
	v_writelane_b32 v254, s0, 4
	v_add_u32_e32 v0, 64, v149
	v_cmp_lt_i32_e32 vcc, v151, v0
	v_writelane_b32 v254, s1, 5
	s_add_u32 s0, s6, 0x3c58a400
	s_addc_u32 s1, s7, 0
	v_writelane_b32 v254, s0, 6
	v_cndmask_b32_e32 v1, v144, v151, vcc
	v_cmp_lt_i32_e32 vcc, v150, v0
	v_writelane_b32 v254, s1, 7
	s_add_u32 s0, s6, 0x3c58a500
	s_addc_u32 s1, s7, 0
	v_writelane_b32 v254, s0, 8
	v_lshlrev_b32_e32 v229, 2, v1
	v_cndmask_b32_e32 v1, v144, v150, vcc
	v_writelane_b32 v254, s1, 9
	s_add_u32 s0, s6, 0x3c58a600
	s_addc_u32 s1, s7, 0
	v_writelane_b32 v254, s0, 10
	v_cmp_lt_i32_e32 vcc, v148, v0
	v_lshlrev_b32_e32 v230, 2, v1
	v_writelane_b32 v254, s1, 11
	s_add_u32 s0, s6, 0x3c58a700
	s_addc_u32 s1, s7, 0
	v_writelane_b32 v254, s0, 12
	v_cndmask_b32_e32 v1, v144, v148, vcc
	v_cmp_lt_i32_e32 vcc, v147, v0
	v_writelane_b32 v254, s1, 13
	s_add_u32 s0, s6, 0x3c58a800
	s_addc_u32 s1, s7, 0
	v_writelane_b32 v254, s0, 14
	v_lshlrev_b32_e32 v231, 2, v1
	v_cndmask_b32_e32 v1, v144, v147, vcc
	v_writelane_b32 v254, s1, 15
	s_add_u32 s0, s6, 0x3c58a900
	s_addc_u32 s1, s7, 0
	v_writelane_b32 v254, s0, 16
	v_lshlrev_b32_e32 v232, 2, v1
	v_cmp_lt_i32_e32 vcc, v146, v0
	v_writelane_b32 v254, s1, 17
	s_add_u32 s0, s6, 0x3c58aa00
	s_addc_u32 s1, s7, 0
	v_writelane_b32 v254, s0, 18
	v_cndmask_b32_e32 v2, v144, v146, vcc
	v_cmp_lt_i32_e32 vcc, v145, v0
	v_writelane_b32 v254, s1, 19
	s_add_u32 s0, s6, 0x3c58ab00
	s_addc_u32 s1, s7, 0
	v_writelane_b32 v254, s0, 20
	v_cndmask_b32_e32 v0, v144, v145, vcc
	v_lshlrev_b32_e32 v234, 2, v0
	v_writelane_b32 v254, s1, 21
	s_add_u32 s0, s6, 0x3c58ac00
	s_addc_u32 s1, s7, 0
	v_writelane_b32 v254, s0, 22
	s_mul_i32 s2, s15, s14
	v_lshlrev_b32_e32 v233, 2, v2
	v_writelane_b32 v254, s1, 23
	s_add_u32 s0, s6, 0x3c58ad00
	s_addc_u32 s1, s7, 0
	v_writelane_b32 v254, s0, 24
	s_mov_b32 s65, 0
	s_movk_i32 s60, 0x100
	v_writelane_b32 v254, s1, 25
	s_add_u32 s0, s6, 0x3c58ae00
	s_addc_u32 s1, s7, 0
	v_writelane_b32 v254, s0, 26
	s_movk_i32 s77, 0x90
	s_movk_i32 s78, 0xffe0
	v_writelane_b32 v254, s1, 27
	s_add_u32 s0, s6, 0x3c58af00
	s_addc_u32 s1, s7, 0
	v_writelane_b32 v254, s0, 28
	v_mov_b32_e32 v235, 0x358637bd
	s_movk_i32 s79, 0x1600
	v_writelane_b32 v254, s1, 29
	s_add_u32 s0, s6, 0x3c58b000
	s_addc_u32 s1, s7, 0
	v_writelane_b32 v254, s0, 30
	s_mov_b32 s22, 0xf800000
	v_mov_b32_e32 v238, 0x260
	v_writelane_b32 v254, s1, 31
	s_add_u32 s0, s6, 0x3c58b100
	s_addc_u32 s1, s7, 0
	v_writelane_b32 v254, s0, 32
	s_movk_i32 s62, 0x110
	v_mov_b32_e32 v241, 0x2000
	v_writelane_b32 v254, s1, 33
	s_add_u32 s0, s6, 0x3c58b200
	s_addc_u32 s1, s7, 0
	v_writelane_b32 v254, s0, 34
	v_mov_b64_e32 v[196:197], 0x200
	v_mov_b64_e32 v[198:199], 0x1ff
	v_writelane_b32 v254, s1, 35
	s_add_u32 s0, s6, 0x3c58b300
	s_addc_u32 s1, s7, 0
	v_writelane_b32 v254, s0, 36
	v_mov_b64_e32 v[250:251], 0xb00
	v_mov_b64_e32 v[202:203], 0xaff
	v_writelane_b32 v254, s1, 37
	s_add_u32 s0, s6, 0x3c58d400
	s_addc_u32 s1, s7, 0
	v_writelane_b32 v254, s0, 38
	v_mov_b32_e32 v239, 0xa0000
	s_mov_b32 s25, 0
	v_writelane_b32 v254, s1, 39
	s_add_u32 s0, s6, 0x3c58d500
	s_addc_u32 s1, s7, 0
	v_writelane_b32 v254, s0, 40
	s_mov_b64 s[68:69], 0x80
	s_mov_b64 s[80:81], 0x20000
	v_writelane_b32 v254, s1, 41
	s_and_b64 s[0:1], s[8:9], exec
	s_cselect_b32 s3, s3, s92
	s_lshl_b32 s0, s3, 3
	s_cmpk_lt_i32 s3, 0x400
	v_writelane_b32 v254, s0, 42
	s_cselect_b64 s[0:1], -1, 0
	v_writelane_b32 v254, s0, 43
	s_cmpk_lt_i32 s3, 0x200
	s_mov_b64 s[82:83], 0x1000
	v_writelane_b32 v254, s1, 44
	s_cselect_b64 s[0:1], -1, 0
	v_writelane_b32 v254, s0, 45
	s_waitcnt lgkmcnt(0)
	s_barrier
; #define INP(i) ldsptr(lds, (i))
; __global__ void __launch_bounds__(512, 2) mega_fwd(Args a) {
;     ...
;                 const gfloat* qn_att = INP(I_QN);
;                 for (int u = vcu; ATT_EN(0) && u < (CH / 256) * 8; u += G) {
;                     const int qb = u % NQB, g4 = (u / NQB) % 4, kvh = (u / NQB / 4) % 2, seq = u / (NQB * 8), head = kvh * 4 + g4;
;                     const size_t tokq = (size_t)seq * S_ + (size_t)qb * 256;
;                     attn_unit<64, 0>(lds, tid, proj + tokq * PROJ + 64 * head, PROJ, proj + (size_t)seq * S_ * PROJ + 512 + 64 * kvh, PROJ,
;                                      vta + ((size_t)(seq * 2 + kvh) * 64) * S_, S_, yb3 + tokq * 512 + 64 * head, 512, 0, S_ / 64,
;                                      0.125f * LOG2E, qb * 256, nullptr, -1e30f, 0.f, qn_att, rope);
	v_writelane_b32 v254, s1, 46
	s_abs_i32 s0, s50
	v_cvt_f32_u32_e32 v1, s0
	s_mul_i32 s1, s2, s33
	v_writelane_b32 v254, s1, 47
	s_sub_i32 s1, 0, s0
	v_rcp_iflag_f32_e32 v1, v1
	s_movk_i32 s33, 0x2800
	v_mul_f32_e32 v0, 0x4f7ffffe, v1
	v_cvt_u32_f32_e32 v0, v0
	v_mov_b32_e32 v1, 0
	v_readfirstlane_b32 s2, v0
	s_mul_i32 s1, s1, s2
	s_mul_hi_u32 s1, s2, s1
	s_add_i32 s2, s2, s1
	s_lshr_b32 s1, s2, 20
	s_mul_i32 s1, s1, s0
	s_sub_i32 s1, 0x1000, s1
	s_sub_i32 s2, s1, s0
	s_cmp_ge_u32 s1, s0
	s_cselect_b32 s1, s2, s1
	s_sub_i32 s2, s1, s0
	s_cmp_ge_u32 s1, s0
	s_cselect_b32 s0, s2, s1
	s_cmp_lg_u32 s0, 0
	s_cselect_b64 s[0:1], -1, 0
	v_writelane_b32 v254, s0, 48
	s_lshl_b32 s12, s14, 4
	s_add_i32 s61, 0, 0x21460
	v_writelane_b32 v254, s1, 49
	s_lshl_b32 s0, s3, 6
	v_writelane_b32 v254, s0, 50
	s_lshl_b32 s0, s14, 6
	v_writelane_b32 v254, s0, 51
	v_writelane_b32 v254, s3, 52
	s_lshl_b32 s0, s3, 7
	v_writelane_b32 v254, s0, 53
	s_add_i32 s0, 0, 0x214b8
	v_writelane_b32 v254, s0, 54
	s_add_i32 s0, 0, 0x21510
	v_writelane_b32 v254, s0, 55
	s_add_i32 s0, 0, 0x21508
	v_writelane_b32 v254, s0, 56
	s_add_i32 s0, 0, 0x2150c
	v_writelane_b32 v254, s0, 57
	s_add_i32 s0, 0, 0x214b0
	v_writelane_b32 v254, s0, 58
	s_add_i32 s0, 0, 0x20000
	v_writelane_b32 v254, s0, 59
	s_add_i32 s0, 0, 0x21450
	v_writelane_b32 v254, s0, 60
	s_add_i32 s0, 0, 0x1b600
	v_writelane_b32 v254, s0, 61
	s_add_i32 s0, 0, 0x21458
	v_writelane_b32 v254, s0, 62
	s_add_i32 s0, 0, 0x21428
	v_writelane_b32 v254, s0, 63
	s_add_i32 s0, 0, 0x21500
	v_writelane_b32 v255, s0, 0
	s_add_i32 s0, 0, 0x21504
	v_writelane_b32 v255, s0, 1
	v_writelane_b32 v255, s92, 2
	v_writelane_b32 v255, s12, 3
	v_writelane_b32 v255, s61, 4
	s_lshl_b32 s19, s14, 7
	s_add_i32 s76, 0, 0x21000
	v_writelane_b32 v255, s50, 5
	v_mov_b32_e32 v246, 0x21450
	ds_read_b128 v[246:249], v246
	v_and_b32_e32 v252, 63, v228
	v_lshlrev_b32_e32 v252, 2, v252
	v_mov_b32_e32 v253, 0
	s_waitcnt lgkmcnt(0)
	v_lshl_add_u64 v[246:247], v[246:247], 0, v[252:253]
	v_lshl_add_u64 v[248:249], v[248:249], 0, v[252:253]
	global_load_dword v246, v[246:247], off
	global_load_dword v248, v[248:249], off
	s_waitcnt vmcnt(0)
	v_and_b32_e32 v246, 0x7fffffff, v246
	v_and_b32_e32 v248, 0x7fffffff, v248
	v_xor_b32_e32 v253, 4, v252
	ds_bpermute_b32 v247, v253, v246
	ds_bpermute_b32 v249, v253, v248
	s_waitcnt lgkmcnt(0)
	v_max_f32_e32 v246, v246, v247
	v_max_f32_e32 v248, v248, v249
	v_xor_b32_e32 v253, 8, v252
	ds_bpermute_b32 v247, v253, v246
	ds_bpermute_b32 v249, v253, v248
	s_waitcnt lgkmcnt(0)
	v_max_f32_e32 v246, v246, v247
	v_max_f32_e32 v248, v248, v249
	v_xor_b32_e32 v253, 16, v252
	ds_bpermute_b32 v247, v253, v246
	ds_bpermute_b32 v249, v253, v248
	s_waitcnt lgkmcnt(0)
	v_max_f32_e32 v246, v246, v247
	v_max_f32_e32 v248, v248, v249
	v_xor_b32_e32 v253, 32, v252
	ds_bpermute_b32 v247, v253, v246
	ds_bpermute_b32 v249, v253, v248
	s_waitcnt lgkmcnt(0)
	v_max_f32_e32 v246, v246, v247
	v_max_f32_e32 v248, v248, v249
	v_xor_b32_e32 v253, 64, v252
	ds_bpermute_b32 v247, v253, v246
	ds_bpermute_b32 v249, v253, v248
	s_waitcnt lgkmcnt(0)
	v_max_f32_e32 v246, v246, v247
	v_max_f32_e32 v248, v248, v249
	v_xor_b32_e32 v253, 128, v252
	ds_bpermute_b32 v247, v253, v246
	ds_bpermute_b32 v249, v253, v248
	s_waitcnt lgkmcnt(0)
	v_max_f32_e32 v246, v246, v247
	v_max_f32_e32 v248, v248, v249
	v_mul_f32_e32 v246, v246, v248
	v_mul_f32_e32 v246, 0x414fbf83, v246
	v_readfirstlane_b32 s0, v246
	v_writelane_b32 v255, s0, 20
	s_branch .LBB0_289
